# L1 invalidates off the critical path: P1 modulation-vector acquire issued before the conversion work; redundant invalidate at the ctx counter wait removed
# baseline (speedup 1.0000x reference)
; #define LAS __attribute__((address_space(3)))
; __device__ __forceinline__ int opaque_tid() { int t = threadIdx.x; asm volatile("" : "+v"(t)); return t; }
; __device__ __forceinline__ void phase1(LAS unsigned char* lds, const Params& P) {
;     const int tid = opaque_tid(), lane = tid & 63, wid = __builtin_amdgcn_readfirstlane(tid >> 6);
;     const int G = gridDim.x;
;     const int gw = blockIdx.x * NWAVES + wid, NGW = G * NWAVES;
;     const float* ADA = (const float*)(P.ws + WS_ADA); bf16_t* HN = (bf16_t*)(P.ws + WS_HN);
;     LAS float* scr = (LAS float*)(lds + wid * 16384);
;     constexpr int I_IN = (DM / 64) * (DIN / 32), I_OUT = (2 * DM / 64) * (DM / 32), I_LRU = 32 * 8;
;     bf16_t* WinT = (bf16_t*)(P.ws + WS_WINT); bf16_t* WoutT = (bf16_t*)(P.ws + WS_WOUTT); bf16_t* LruW = (bf16_t*)(P.ws + WS_LRUW);
;     for (int it = gw; it < I_IN + I_OUT + I_LRU; it += NGW) {
;         int r = it;
;         if (r < I_IN) { p0_transpose_item<true>(P.w_in, DM, DIN, WinT, 1.0f, scr, r, lane); continue; } r -= I_IN;
;     ...
;     if (wid == 0) { unsigned sp = 0;
;         while ((unsigned)__builtin_amdgcn_readfirstlane(__hip_atomic_load((unsigned*)(P.ws + WS_ADA_CNT), __ATOMIC_RELAXED, __HIP_MEMORY_SCOPE_AGENT)) < 192u) { __builtin_amdgcn_s_sleep(1); if (++sp > (1u << 20)) break; }
;         __builtin_amdgcn_fence(__ATOMIC_ACQUIRE, "agent");
;         asm volatile("s_waitcnt vmcnt(0)" ::: "memory"); }
.LBB0_33:
	s_waitcnt vmcnt(5)
	v_mov_b32_e32 v17, v167
	s_nop 0
	v_readfirstlane_b32 s79, v17
	s_cmp_gt_u32 s79, 63
	s_cbranch_scc1 .Lp1_noinv
	buffer_inv sc1
.Lp1_noinv:
	s_ashr_i32 s0, s79, 6
	v_and_b32_e32 v162, 63, v17
	s_add_i32 s78, s0, s2
	s_cmpk_gt_i32 s78, 0xeff
	v_lshlrev_b32_e32 v16, 3, v162
	s_cbranch_scc1 .LBB0_52
	s_lshl_b32 s1, s0, 14
	v_lshrrev_b32_e32 v18, 5, v162
	v_and_b32_e32 v19, 31, v17
	s_add_i32 s1, s1, 0
	v_lshlrev_b32_e32 v4, 2, v19
	v_mul_u32_u24_e32 v0, 0x84, v18
	s_waitcnt vmcnt(4)
	v_lshrrev_b32_e32 v21, 3, v162
	v_and_b32_e32 v6, 56, v16
	v_add3_u32 v20, s1, v4, v0
	v_mul_u32_u24_e32 v0, 0x84, v6
	v_lshlrev_b32_e32 v1, 2, v21
	v_add3_u32 v22, s1, v0, v1
	s_bfe_u32 s1, s79, 0x30006
	s_lshl_b32 s44, s1, 5
	s_add_i32 s76, s44, 0xff80
	s_cmp_lt_u32 s1, 4
	s_cselect_b32 s1, s44, s76
	s_and_b32 s1, s1, 0xffe0
	v_or_b32_e32 v23, 8, v21
	v_or_b32_e32 v5, s1, v21
	v_or_b32_e32 v24, 16, v21
	v_lshlrev_b32_e32 v8, 7, v5
	v_or_b32_e32 v5, s1, v23
	v_or_b32_e32 v25, 24, v21
	v_lshlrev_b32_e32 v10, 7, v5
	v_or_b32_e32 v5, s1, v24
	v_lshlrev_b32_e32 v12, 7, v5
	v_or_b32_e32 v5, s1, v25
	v_lshlrev_b32_e32 v160, 1, v6
	v_lshlrev_b32_e32 v14, 7, v5
	v_mov_b32_e32 v5, v161
	s_lshl_b32 s0, s0, 5
	v_lshl_add_u64 v[0:1], s[18:19], 0, v[160:161]
	v_lshl_add_u64 v[2:3], s[20:21], 0, v[160:161]
	v_or_b32_e32 v26, s1, v19
	v_lshl_add_u64 v[4:5], s[50:51], 0, v[4:5]
	s_add_i32 s80, s27, s0
	v_lshlrev_b32_e32 v6, 1, v6
	v_lshlrev_b32_e32 v8, 1, v8
	v_lshlrev_b32_e32 v10, 1, v10
	v_lshlrev_b32_e32 v12, 1, v12
	v_lshlrev_b32_e32 v14, 1, v14
	v_add_u32_e32 v27, 0x400, v20
	v_add_u32_e32 v28, 0x800, v20
	v_add_u32_e32 v29, 0xc00, v20
	v_add_u32_e32 v30, 0x1000, v20
	v_add_u32_e32 v31, 0x1400, v20
	v_add_u32_e32 v32, 0x1800, v20
	v_add_u32_e32 v33, 0x1c00, v20
	s_mov_b32 s81, s78
	s_branch .LBB0_37

; __device__ __forceinline__ void phase1(LAS unsigned char* lds, const Params& P) {
;     ...
;     if (wid == 0) { unsigned sp = 0;
;         while ((unsigned)__builtin_amdgcn_readfirstlane(__hip_atomic_load((unsigned*)(P.ws + WS_ADA_CNT), __ATOMIC_RELAXED, __HIP_MEMORY_SCOPE_AGENT)) < 192u) { __builtin_amdgcn_s_sleep(1); if (++sp > (1u << 20)) break; }
;         __builtin_amdgcn_fence(__ATOMIC_ACQUIRE, "agent");
;         asm volatile("s_waitcnt vmcnt(0)" ::: "memory"); }
.LBB0_60:
	s_waitcnt lgkmcnt(0)
	s_waitcnt vmcnt(0)

; __global__ void __launch_bounds__(NTHREADS, 2) fwd_megakernel(Params P) {
;     ...
;         __syncthreads();
;         if (threadIdx.x < 64) { unsigned sp = 0;
;             asm volatile("s_waitcnt vmcnt(0)\n\tbuffer_inv sc1" ::: "memory");
;             while ((unsigned)__builtin_amdgcn_readfirstlane(__hip_atomic_load((unsigned*)(P.ws + WS_CTX_CNT), __ATOMIC_RELAXED, __HIP_MEMORY_SCOPE_AGENT)) < (unsigned)ctxB) { __builtin_amdgcn_s_sleep(1); if (++sp > (1u << 20)) break; }
;             asm volatile("s_waitcnt vmcnt(0)" ::: "memory"); }
.LBB0_269:
	v_cmp_gt_u32_e32 vcc, 64, v167
	s_waitcnt vmcnt(0) lgkmcnt(0)
	s_barrier
	s_and_saveexec_b64 s[0:1], vcc
	s_cbranch_execz .LBB0_275
	s_waitcnt vmcnt(0)
	s_add_u32 s4, s22, 0x88080
	s_addc_u32 s5, s23, 0
	s_mov_b32 s3, 0x100001
	v_mov_b32_e32 v0, 0
	s_branch .LBB0_272
